# RG-LRU sub-block: depthwise-conv tap rows prefetched from LDS in batches (one wait instead of one per tap)
# baseline (speedup 1.0000x reference)
.LBB0_207:
	s_waitcnt lgkmcnt(0)
	ds_read_b128 v[222:225], v180 offset:11008
	ds_read_b128 v[226:229], v180 offset:11152
	ds_read_b128 v[230:233], v180 offset:11296
	ds_read_b128 v[234:237], v180 offset:11440
	ds_read_b128 v[238:241], v180 offset:12160
	ds_read_b128 v[242:245], v180 offset:12304
	ds_read_b128 v[246:249], v180 offset:12448
	ds_read_b128 v[250:253], v180 offset:12592
	s_add_i32 s43, s43, 16
	s_cmpk_lg_i32 s43, 0x80
	s_waitcnt lgkmcnt(0)
	v_lshlrev_b32_e32 v124, 16, v222
	v_and_b32_e32 v125, 0xffff0000, v222
	v_lshlrev_b32_e32 v120, 16, v223
	v_and_b32_e32 v121, 0xffff0000, v223
	v_lshlrev_b32_e32 v126, 16, v224
	v_and_b32_e32 v127, 0xffff0000, v224
	v_lshlrev_b32_e32 v122, 16, v225
	v_and_b32_e32 v123, 0xffff0000, v225
	v_pk_fma_f32 v[128:129], v[6:7], v[120:121], v[22:23]
	v_pk_fma_f32 v[130:131], v[2:3], v[122:123], v[18:19]
	v_pk_fma_f32 v[124:125], v[4:5], v[124:125], v[20:21]
	v_pk_fma_f32 v[126:127], v[0:1], v[126:127], v[16:17]
	s_waitcnt lgkmcnt(0)
	v_lshlrev_b32_e32 v132, 16, v226
	v_and_b32_e32 v133, 0xffff0000, v226
	v_lshlrev_b32_e32 v120, 16, v227
	v_and_b32_e32 v121, 0xffff0000, v227
	v_lshlrev_b32_e32 v134, 16, v228
	v_and_b32_e32 v135, 0xffff0000, v228
	v_lshlrev_b32_e32 v122, 16, v229
	v_and_b32_e32 v123, 0xffff0000, v229
	v_pk_fma_f32 v[128:129], v[14:15], v[120:121], v[128:129]
	v_pk_fma_f32 v[130:131], v[10:11], v[122:123], v[130:131]
	v_pk_fma_f32 v[124:125], v[12:13], v[132:133], v[124:125]
	v_pk_fma_f32 v[126:127], v[8:9], v[134:135], v[126:127]
	s_waitcnt lgkmcnt(0)
	v_lshlrev_b32_e32 v132, 16, v230
	v_and_b32_e32 v133, 0xffff0000, v230
	v_lshlrev_b32_e32 v120, 16, v231
	v_and_b32_e32 v121, 0xffff0000, v231
	v_lshlrev_b32_e32 v134, 16, v232
	v_and_b32_e32 v135, 0xffff0000, v232
	v_lshlrev_b32_e32 v122, 16, v233
	v_and_b32_e32 v123, 0xffff0000, v233
	v_pk_fma_f32 v[124:125], v[24:25], v[132:133], v[124:125]
	v_pk_fma_f32 v[128:129], v[26:27], v[120:121], v[128:129]
	v_pk_fma_f32 v[132:133], v[28:29], v[134:135], v[126:127]
	v_pk_fma_f32 v[126:127], v[30:31], v[122:123], v[130:131]
	s_waitcnt lgkmcnt(0)
	v_lshlrev_b32_e32 v130, 16, v234
	v_and_b32_e32 v131, 0xffff0000, v234
	v_lshlrev_b32_e32 v120, 16, v235
	v_and_b32_e32 v121, 0xffff0000, v235
	v_lshlrev_b32_e32 v134, 16, v236
	v_and_b32_e32 v135, 0xffff0000, v236
	v_lshlrev_b32_e32 v136, 16, v237
	v_and_b32_e32 v137, 0xffff0000, v237
	v_pk_fma_f32 v[122:123], v[34:35], v[120:121], v[128:129]
	v_pk_fma_f32 v[120:121], v[32:33], v[130:131], v[124:125]
	v_pk_fma_f32 v[126:127], v[38:39], v[136:137], v[126:127]
	v_pk_fma_f32 v[124:125], v[36:37], v[134:135], v[132:133]
	ds_write_b128 v179, v[120:123] offset:2304
	ds_write_b128 v179, v[124:127] offset:2320
	v_cvt_pk_bf16_f32 v120, v120, v121
	v_cvt_pk_bf16_f32 v121, v122, v123
	v_cvt_pk_bf16_f32 v122, v124, v125
	v_cvt_pk_bf16_f32 v123, v126, v127
	ds_write_b128 v180, v[120:123]
	s_waitcnt lgkmcnt(0)
	v_lshlrev_b32_e32 v124, 16, v238
	v_and_b32_e32 v125, 0xffff0000, v238
	v_lshlrev_b32_e32 v120, 16, v239
	v_and_b32_e32 v121, 0xffff0000, v239
	v_lshlrev_b32_e32 v126, 16, v240
	v_and_b32_e32 v127, 0xffff0000, v240
	v_lshlrev_b32_e32 v122, 16, v241
	v_and_b32_e32 v123, 0xffff0000, v241
	v_pk_fma_f32 v[128:129], v[6:7], v[120:121], v[22:23]
	v_pk_fma_f32 v[130:131], v[2:3], v[122:123], v[18:19]
	v_pk_fma_f32 v[124:125], v[4:5], v[124:125], v[20:21]
	v_pk_fma_f32 v[126:127], v[0:1], v[126:127], v[16:17]
	s_waitcnt lgkmcnt(0)
	v_lshlrev_b32_e32 v132, 16, v242
	v_and_b32_e32 v133, 0xffff0000, v242
	v_lshlrev_b32_e32 v120, 16, v243
	v_and_b32_e32 v121, 0xffff0000, v243
	v_lshlrev_b32_e32 v134, 16, v244
	v_and_b32_e32 v135, 0xffff0000, v244
	v_lshlrev_b32_e32 v122, 16, v245
	v_and_b32_e32 v123, 0xffff0000, v245
	v_pk_fma_f32 v[128:129], v[14:15], v[120:121], v[128:129]
	v_pk_fma_f32 v[130:131], v[10:11], v[122:123], v[130:131]
	v_pk_fma_f32 v[124:125], v[12:13], v[132:133], v[124:125]
	v_pk_fma_f32 v[126:127], v[8:9], v[134:135], v[126:127]
	s_waitcnt lgkmcnt(0)
	v_lshlrev_b32_e32 v132, 16, v246
	v_and_b32_e32 v133, 0xffff0000, v246
	v_lshlrev_b32_e32 v120, 16, v247
	v_and_b32_e32 v121, 0xffff0000, v247
	v_lshlrev_b32_e32 v134, 16, v248
	v_and_b32_e32 v135, 0xffff0000, v248
	v_lshlrev_b32_e32 v122, 16, v249
	v_and_b32_e32 v123, 0xffff0000, v249
	v_pk_fma_f32 v[124:125], v[24:25], v[132:133], v[124:125]
	v_pk_fma_f32 v[128:129], v[26:27], v[120:121], v[128:129]
	v_pk_fma_f32 v[132:133], v[28:29], v[134:135], v[126:127]
	v_pk_fma_f32 v[126:127], v[30:31], v[122:123], v[130:131]
	s_waitcnt lgkmcnt(0)
	v_lshlrev_b32_e32 v130, 16, v250
	v_and_b32_e32 v131, 0xffff0000, v250
	v_lshlrev_b32_e32 v120, 16, v251
	v_and_b32_e32 v121, 0xffff0000, v251
	v_lshlrev_b32_e32 v134, 16, v252
	v_and_b32_e32 v135, 0xffff0000, v252
	v_lshlrev_b32_e32 v136, 16, v253
	v_and_b32_e32 v137, 0xffff0000, v253
	v_pk_fma_f32 v[122:123], v[34:35], v[120:121], v[128:129]
	v_pk_fma_f32 v[120:121], v[32:33], v[130:131], v[124:125]
	v_pk_fma_f32 v[126:127], v[38:39], v[136:137], v[126:127]
	v_pk_fma_f32 v[124:125], v[36:37], v[134:135], v[132:133]
	ds_write_b128 v179, v[120:123] offset:4480
	ds_write_b128 v179, v[124:127] offset:4496
	v_cvt_pk_bf16_f32 v120, v120, v121
	v_cvt_pk_bf16_f32 v121, v122, v123
	v_cvt_pk_bf16_f32 v122, v124, v125
	v_cvt_pk_bf16_f32 v123, v126, v127
	ds_write_b128 v180, v[120:123] offset:1152
	s_waitcnt lgkmcnt(0)
	ds_read_b128 v[120:123], v173
	ds_read_b128 v[222:225], v173 offset:64
	s_waitcnt lgkmcnt(1)
	v_mfma_f32_16x16x32_bf16 v[124:127], v[120:123], v[40:43], 0
	s_waitcnt lgkmcnt(0)
	v_mfma_f32_16x16x32_bf16 v[226:229], v[222:225], v[44:47], v[124:127]
	v_mfma_f32_16x16x32_bf16 v[124:127], v[120:123], v[48:51], 0
	v_mfma_f32_16x16x32_bf16 v[128:131], v[120:123], v[72:75], 0
	s_nop 5
	v_add_f32_e32 v165, v161, v226
	v_mul_f32_e32 v165, 0xbfb8aa3b, v165
	v_exp_f32_e32 v165, v165
	v_mfma_f32_16x16x32_bf16 v[136:139], v[222:225], v[52:55], v[124:127]
	v_add_f32_e32 v165, 1.0, v165
	v_mfma_f32_16x16x32_bf16 v[124:127], v[120:123], v[56:59], 0
	v_rcp_f32_e32 v165, v165
	s_nop 4
	v_add_f32_e32 v136, v181, v136
	v_mul_f32_e32 v136, 0xbfb8aa3b, v136
	v_mfma_f32_16x16x32_bf16 v[230:233], v[222:225], v[76:79], v[128:131]
	v_mul_f32_e32 v165, v98, v165
	v_mul_f32_e32 v170, 0x3fb8aa3b, v165
	v_add_f32_e32 v165, v165, v165
	v_mfma_f32_16x16x32_bf16 v[128:131], v[120:123], v[80:83], 0
	v_exp_f32_e32 v136, v136
	s_nop 2
	v_add_f32_e32 v168, v163, v230
	v_mul_f32_e32 v168, 0xbfb8aa3b, v168
	v_mfma_f32_16x16x32_bf16 v[132:135], v[222:225], v[60:63], v[124:127]
	v_exp_f32_e32 v168, v168
	v_add_f32_e32 v136, 1.0, v136
	v_rcp_f32_e32 v136, v136
	v_mfma_f32_16x16x32_bf16 v[124:127], v[120:123], v[64:67], 0
	v_add_f32_e32 v168, 1.0, v168
	v_rcp_f32_e32 v168, v168
	v_mul_f32_e32 v136, v193, v136
	v_mfma_f32_16x16x32_bf16 v[140:143], v[222:225], v[84:87], v[128:131]
	v_add_f32_e32 v138, v181, v138
	v_mul_f32_e32 v138, 0xbfb8aa3b, v138
	v_exp_f32_e32 v138, v138
	v_mfma_f32_16x16x32_bf16 v[128:131], v[120:123], v[88:91], 0
	v_add_f32_e32 v132, v189, v132
	s_nop 2
	v_add_f32_e32 v140, v188, v140
	v_mul_f32_e32 v140, 0xbfb8aa3b, v140
	v_mfma_f32_16x16x32_bf16 v[120:123], v[120:123], v[100:103], 0
	v_exp_f32_e32 v140, v140
	v_add_f32_e32 v138, 1.0, v138
	v_rcp_f32_e32 v138, v138
	v_mfma_f32_16x16x32_bf16 v[124:127], v[222:225], v[68:71], v[124:127]
	v_add_f32_e32 v140, 1.0, v140
	v_rcp_f32_e32 v140, v140
	v_mul_f32_e32 v138, v193, v138
	v_mfma_f32_16x16x32_bf16 v[128:131], v[222:225], v[92:95], v[128:131]
	v_mul_f32_e32 v132, 0xbfb8aa3b, v132
	v_exp_f32_e32 v132, v132
	s_nop 1
	v_add_f32_e32 v124, v192, v124
	v_mfma_f32_16x16x32_bf16 v[120:123], v[222:225], v[104:107], v[120:123]
	v_exp_f32_e32 v222, v170
	v_fmamk_f32 v170, v165, 0x37d00d01, v198
	v_fmaak_f32 v170, v165, v170, 0x3ab60b61
	v_fmaak_f32 v170, v165, v170, 0x3c088889
	v_fmaak_f32 v170, v165, v170, 0x3d2aaaab
	v_fmaak_f32 v170, v165, v170, 0x3e2aaaab
	v_fma_f32 v170, v165, v170, 0.5
	v_fma_f32 v223, v165, v170, 1.0
	v_mul_f32_e64 v165, v165, -v223
	v_add_u32_e32 v224, 0x800, v175
	v_max_f32_e32 v165, 0, v165
	ds_read2_b32 v[170:171], v224 offset0:64 offset1:80
	v_sqrt_f32_e32 v165, v165
	v_add_f32_e32 v132, 1.0, v132
	v_rcp_f32_e32 v132, v132
	v_add_f32_e32 v128, v190, v128
	v_mul_f32_e32 v165, v168, v165
	s_waitcnt lgkmcnt(0)
	v_mul_f32_e32 v165, v170, v165
	ds_write_b32 v175, v222 offset:6656
	ds_write_b32 v175, v165 offset:2304
	v_add_f32_e32 v165, v161, v227
	v_mul_f32_e32 v165, 0xbfb8aa3b, v165
	v_exp_f32_e32 v165, v165
	v_add_f32_e32 v168, v163, v231
	v_mul_f32_e32 v168, 0xbfb8aa3b, v168
	v_exp_f32_e32 v168, v168
	v_add_f32_e32 v165, 1.0, v165
	v_rcp_f32_e32 v165, v165
	v_mul_f32_e32 v132, v220, v132
	v_add_f32_e32 v168, 1.0, v168
	v_rcp_f32_e32 v168, v168
	v_mul_f32_e32 v165, v98, v165
	v_mul_f32_e32 v170, 0x3fb8aa3b, v165
	v_add_f32_e32 v165, v165, v165
	v_fmamk_f32 v222, v165, 0x37d00d01, v198
	v_fmaak_f32 v222, v165, v222, 0x3ab60b61
	v_fmaak_f32 v222, v165, v222, 0x3c088889
	v_fmaak_f32 v222, v165, v222, 0x3d2aaaab
	v_fmaak_f32 v222, v165, v222, 0x3e2aaaab
	v_fma_f32 v222, v165, v222, 0.5
	v_fma_f32 v225, v165, v222, 1.0
	v_mul_f32_e64 v165, v165, -v225
	v_max_f32_e32 v165, 0, v165
	v_sqrt_f32_e32 v165, v165
	ds_read2_b32 v[222:223], v224 offset0:132 offset1:200
	v_exp_f32_e32 v170, v170
	v_mul_f32_e32 v128, 0xbfb8aa3b, v128
	v_mul_f32_e32 v165, v168, v165
	v_add_f32_e32 v168, v161, v228
	v_mul_f32_e32 v168, 0xbfb8aa3b, v168
	v_exp_f32_e32 v168, v168
	s_waitcnt lgkmcnt(0)
	v_mul_f32_e32 v165, v222, v165
	v_add_f32_e32 v222, v163, v232
	v_mul_f32_e32 v222, 0xbfb8aa3b, v222
	v_add_f32_e32 v168, 1.0, v168
	v_rcp_f32_e32 v168, v168
	v_exp_f32_e32 v222, v222
	v_exp_f32_e32 v128, v128
	v_add_f32_e32 v129, v190, v129
	v_mul_f32_e32 v168, v98, v168
	v_mul_f32_e32 v225, 0x3fb8aa3b, v168
	v_add_f32_e32 v168, v168, v168
	v_fmamk_f32 v226, v168, 0x37d00d01, v198
	v_fmaak_f32 v226, v168, v226, 0x3ab60b61
	v_fmaak_f32 v226, v168, v226, 0x3c088889
	v_fmaak_f32 v226, v168, v226, 0x3d2aaaab
	v_fmaak_f32 v226, v168, v226, 0x3e2aaaab
	v_fma_f32 v226, v168, v226, 0.5
	v_fma_f32 v226, v168, v226, 1.0
	v_mul_f32_e64 v168, v168, -v226
	v_add_f32_e32 v222, 1.0, v222
	v_max_f32_e32 v168, 0, v168
	v_rcp_f32_e32 v222, v222
	v_sqrt_f32_e32 v168, v168
	v_exp_f32_e32 v225, v225
	v_add_f32_e32 v128, 1.0, v128
	v_rcp_f32_e32 v128, v128
	v_mul_f32_e32 v168, v222, v168
	v_add_u32_e32 v222, 0x1a00, v175
	v_mul_f32_e32 v168, v223, v168
	ds_write2_b32 v222, v170, v225 offset0:68 offset1:136
	ds_write2_b32 v224, v165, v168 offset0:132 offset1:200
	v_add_f32_e32 v165, v161, v229
	v_mul_f32_e32 v165, 0xbfb8aa3b, v165
	v_exp_f32_e32 v165, v165
	v_add_f32_e32 v168, v163, v233
	v_mul_f32_e32 v168, 0xbfb8aa3b, v168
	v_exp_f32_e32 v168, v168
	v_add_f32_e32 v165, 1.0, v165
	v_rcp_f32_e32 v165, v165
	ds_read_b32 v223, v175 offset:3120
	v_add_f32_e32 v168, 1.0, v168
	v_rcp_f32_e32 v168, v168
	v_mul_f32_e32 v165, v98, v165
	v_mul_f32_e32 v170, 0x3fb8aa3b, v165
	v_add_f32_e32 v165, v165, v165
	v_fmamk_f32 v222, v165, 0x37d00d01, v198
	v_fmaak_f32 v222, v165, v222, 0x3ab60b61
	v_fmaak_f32 v222, v165, v222, 0x3c088889
	v_fmaak_f32 v222, v165, v222, 0x3d2aaaab
	v_fmaak_f32 v222, v165, v222, 0x3e2aaaab
	v_fma_f32 v222, v165, v222, 0.5
	v_fma_f32 v222, v165, v222, 1.0
	v_mul_f32_e64 v165, v165, -v222
	v_max_f32_e32 v165, 0, v165
	v_sqrt_f32_e32 v165, v165
	v_exp_f32_e32 v170, v170
	v_mul_f32_e32 v129, 0xbfb8aa3b, v129
	v_exp_f32_e32 v129, v129
	v_mul_f32_e32 v165, v168, v165
	s_waitcnt lgkmcnt(0)
	v_mul_f32_e32 v165, v223, v165
	ds_write_b32 v175, v170 offset:7472
	ds_write_b32 v175, v165 offset:3120
	v_mul_f32_e32 v165, 0x3fb8aa3b, v136
	v_add_f32_e32 v136, v136, v136
	v_fmamk_f32 v168, v136, 0x37d00d01, v198
	v_fmaak_f32 v168, v136, v168, 0x3ab60b61
	v_fmaak_f32 v168, v136, v168, 0x3c088889
	v_fmaak_f32 v168, v136, v168, 0x3d2aaaab
	v_fmaak_f32 v168, v136, v168, 0x3e2aaaab
	v_fma_f32 v168, v136, v168, 0.5
	v_fma_f32 v168, v136, v168, 1.0
	v_mul_f32_e64 v136, v136, -v168
	v_max_f32_e32 v136, 0, v136
	v_sqrt_f32_e32 v136, v136
	v_exp_f32_e32 v165, v165
	v_add_u32_e32 v170, 0x800, v176
	v_add_f32_e32 v129, 1.0, v129
	v_mul_f32_e32 v136, v140, v136
	v_mul_f32_e32 v136, v171, v136
	ds_write_b32 v175, v165 offset:6720
	ds_write_b32 v175, v136 offset:2368
	v_add_f32_e32 v136, v181, v137
	v_mul_f32_e32 v136, 0xbfb8aa3b, v136
	v_exp_f32_e32 v136, v136
	v_add_f32_e32 v137, v188, v141
	v_mul_f32_e32 v137, 0xbfb8aa3b, v137
	v_exp_f32_e32 v137, v137
	v_add_f32_e32 v136, 1.0, v136
	v_rcp_f32_e32 v136, v136
	v_add_f32_e32 v130, v190, v130
	v_add_f32_e32 v137, 1.0, v137
	v_rcp_f32_e32 v140, v137
	v_mul_f32_e32 v136, v193, v136
	v_add_f32_e32 v165, v136, v136
	v_mul_f32_e32 v137, 0x3fb8aa3b, v136
	v_fmamk_f32 v136, v165, 0x37d00d01, v198
	v_fmaak_f32 v136, v165, v136, 0x3ab60b61
	v_fmaak_f32 v136, v165, v136, 0x3c088889
	v_fmaak_f32 v136, v165, v136, 0x3d2aaaab
	v_fmaak_f32 v136, v165, v136, 0x3e2aaaab
	v_fma_f32 v136, v165, v136, 0.5
	v_fma_f32 v168, v165, v136, 1.0
	v_mul_f32_e64 v165, v165, -v168
	v_max_f32_e32 v165, 0, v165
	v_exp_f32_e32 v141, v137
	ds_read2_b32 v[136:137], v170 offset0:132 offset1:200
	v_sqrt_f32_e32 v165, v165
	v_mul_f32_e32 v130, 0xbfb8aa3b, v130
	v_exp_f32_e32 v130, v130
	v_mul_f32_e32 v124, 0xbfb8aa3b, v124
	v_mul_f32_e32 v140, v140, v165
	s_waitcnt lgkmcnt(0)
	v_mul_f32_e32 v136, v140, v136
	v_add_f32_e32 v140, v188, v142
	v_mul_f32_e32 v142, 0x3fb8aa3b, v138
	v_add_f32_e32 v138, v138, v138
	v_fmamk_f32 v165, v138, 0x37d00d01, v198
	v_fmaak_f32 v165, v138, v165, 0x3ab60b61
	v_fmaak_f32 v165, v138, v165, 0x3c088889
	v_mul_f32_e32 v140, 0xbfb8aa3b, v140
	v_fmaak_f32 v165, v138, v165, 0x3d2aaaab
	v_exp_f32_e32 v140, v140
	v_fmaak_f32 v165, v138, v165, 0x3e2aaaab
	v_fma_f32 v165, v138, v165, 0.5
	v_fma_f32 v165, v138, v165, 1.0
	v_mul_f32_e64 v138, v138, -v165
	v_add_f32_e32 v140, 1.0, v140
	v_max_f32_e32 v138, 0, v138
	v_rcp_f32_e32 v140, v140
	v_sqrt_f32_e32 v138, v138
	v_exp_f32_e32 v142, v142
	v_add_f32_e32 v130, 1.0, v130
	v_rcp_f32_e32 v130, v130
	v_mul_f32_e32 v138, v140, v138
	v_mul_f32_e32 v137, v138, v137
	v_add_u32_e32 v138, 0x1a00, v176
	ds_write2_b32 v138, v141, v142 offset0:68 offset1:136
	ds_write2_b32 v170, v136, v137 offset0:132 offset1:200
	v_add_f32_e32 v136, v181, v139
	v_mul_f32_e32 v136, 0xbfb8aa3b, v136
	v_exp_f32_e32 v136, v136
	ds_read_b32 v140, v176 offset:3120
	v_exp_f32_e32 v124, v124
	v_add_f32_e32 v120, v191, v120
	v_add_f32_e32 v136, 1.0, v136
	v_rcp_f32_e32 v137, v136
	v_add_f32_e32 v136, v188, v143
	v_mul_f32_e32 v136, 0xbfb8aa3b, v136
	v_exp_f32_e32 v136, v136
	v_mul_f32_e32 v138, v193, v137
	v_mul_f32_e32 v137, 0x3fb8aa3b, v138
	v_add_f32_e32 v138, v138, v138
	v_fmamk_f32 v139, v138, 0x37d00d01, v198
	v_fmaak_f32 v139, v138, v139, 0x3ab60b61
	v_fmaak_f32 v139, v138, v139, 0x3c088889
	v_fmaak_f32 v139, v138, v139, 0x3d2aaaab
	v_fmaak_f32 v139, v138, v139, 0x3e2aaaab
	v_fma_f32 v139, v138, v139, 0.5
	v_fma_f32 v139, v138, v139, 1.0
	v_mul_f32_e64 v138, v138, -v139
	v_add_f32_e32 v136, 1.0, v136
	v_max_f32_e32 v138, 0, v138
	v_rcp_f32_e32 v136, v136
	v_sqrt_f32_e32 v138, v138
	v_exp_f32_e32 v137, v137
	v_add_f32_e32 v124, 1.0, v124
	v_rcp_f32_e32 v124, v124
	v_mul_f32_e32 v136, v136, v138
	s_waitcnt lgkmcnt(0)
	v_mul_f32_e32 v136, v136, v140
	ds_write_b32 v176, v137 offset:7472
	ds_write_b32 v176, v136 offset:3120
	v_mul_f32_e32 v136, 0x3fb8aa3b, v132
	v_add_f32_e32 v132, v132, v132
	v_fmamk_f32 v137, v132, 0x37d00d01, v198
	v_fmaak_f32 v137, v132, v137, 0x3ab60b61
	v_fmaak_f32 v137, v132, v137, 0x3c088889
	v_fmaak_f32 v137, v132, v137, 0x3d2aaaab
	v_fmaak_f32 v137, v132, v137, 0x3e2aaaab
	v_fma_f32 v137, v132, v137, 0.5
	v_fma_f32 v137, v132, v137, 1.0
	v_mul_f32_e64 v132, v132, -v137
	v_max_f32_e32 v132, 0, v132
	ds_read_b32 v138, v175 offset:2432
	v_sqrt_f32_e32 v132, v132
	v_exp_f32_e32 v136, v136
	v_mul_f32_e32 v124, v221, v124
	v_mul_f32_e32 v120, 0xbfb8aa3b, v120
	v_mul_f32_e32 v128, v128, v132
	s_waitcnt lgkmcnt(0)
	v_mul_f32_e32 v128, v128, v138
	ds_write_b32 v175, v136 offset:6784
	ds_write_b32 v175, v128 offset:2432
	v_add_f32_e32 v128, v189, v133
	v_mul_f32_e32 v128, 0xbfb8aa3b, v128
	v_exp_f32_e32 v128, v128
	v_rcp_f32_e32 v132, v129
	v_add_u32_e32 v138, 0x800, v177
	v_exp_f32_e32 v120, v120
	v_add_f32_e32 v128, 1.0, v128
	v_rcp_f32_e32 v128, v128
	v_add_f32_e32 v121, v191, v121
	v_add_f32_e32 v120, 1.0, v120
	v_rcp_f32_e32 v120, v120
	v_mul_f32_e32 v128, v220, v128
	v_add_f32_e32 v136, v128, v128
	v_mul_f32_e32 v129, 0x3fb8aa3b, v128
	v_fmamk_f32 v128, v136, 0x37d00d01, v198
	v_fmaak_f32 v128, v136, v128, 0x3ab60b61
	v_fmaak_f32 v128, v136, v128, 0x3c088889
	v_fmaak_f32 v128, v136, v128, 0x3d2aaaab
	v_fmaak_f32 v128, v136, v128, 0x3e2aaaab
	v_fma_f32 v128, v136, v128, 0.5
	v_fma_f32 v137, v136, v128, 1.0
	v_mul_f32_e64 v136, v136, -v137
	v_max_f32_e32 v136, 0, v136
	v_exp_f32_e32 v133, v129
	ds_read2_b32 v[128:129], v138 offset0:132 offset1:200
	v_sqrt_f32_e32 v136, v136
	v_mul_f32_e32 v121, 0xbfb8aa3b, v121
	v_exp_f32_e32 v121, v121
	v_add_f32_e32 v123, v191, v123
	v_mul_f32_e32 v132, v132, v136
	s_waitcnt lgkmcnt(0)
	v_mul_f32_e32 v128, v132, v128
	v_add_f32_e32 v132, v189, v134
	v_mul_f32_e32 v132, 0xbfb8aa3b, v132
	v_exp_f32_e32 v132, v132
	v_add_f32_e32 v121, 1.0, v121
	v_rcp_f32_e32 v121, v121
	v_mul_f32_e32 v123, 0xbfb8aa3b, v123
	v_add_f32_e32 v132, 1.0, v132
	v_rcp_f32_e32 v132, v132
	v_exp_f32_e32 v123, v123
	v_mul_f32_e32 v132, v220, v132
	v_mul_f32_e32 v134, 0x3fb8aa3b, v132
	v_add_f32_e32 v132, v132, v132
	v_fmamk_f32 v136, v132, 0x37d00d01, v198
	v_fmaak_f32 v136, v132, v136, 0x3ab60b61
	v_fmaak_f32 v136, v132, v136, 0x3c088889
	v_fmaak_f32 v136, v132, v136, 0x3d2aaaab
	v_fmaak_f32 v136, v132, v136, 0x3e2aaaab
	v_fma_f32 v136, v132, v136, 0.5
	v_fma_f32 v136, v132, v136, 1.0
	v_mul_f32_e64 v132, v132, -v136
	v_max_f32_e32 v132, 0, v132
	v_sqrt_f32_e32 v132, v132
	v_exp_f32_e32 v134, v134
	v_add_f32_e32 v123, 1.0, v123
	v_rcp_f32_e32 v123, v123
	v_mul_f32_e32 v130, v130, v132
	v_mul_f32_e32 v129, v130, v129
	v_add_u32_e32 v130, 0x1a00, v177
	ds_write2_b32 v130, v133, v134 offset0:68 offset1:136
	ds_write2_b32 v138, v128, v129 offset0:132 offset1:200
	v_add_f32_e32 v128, v189, v135
	v_mul_f32_e32 v128, 0xbfb8aa3b, v128
	v_exp_f32_e32 v128, v128
	v_add_f32_e32 v129, v190, v131
	v_mul_f32_e32 v129, 0xbfb8aa3b, v129
	v_exp_f32_e32 v129, v129
	v_add_f32_e32 v128, 1.0, v128
	v_rcp_f32_e32 v128, v128
	ds_read_b32 v132, v177 offset:3120
	v_add_f32_e32 v129, 1.0, v129
	v_rcp_f32_e32 v129, v129
	v_mul_f32_e32 v128, v220, v128
	v_mul_f32_e32 v130, 0x3fb8aa3b, v128
	v_add_f32_e32 v128, v128, v128
	v_fmamk_f32 v131, v128, 0x37d00d01, v198
	v_fmaak_f32 v131, v128, v131, 0x3ab60b61
	v_fmaak_f32 v131, v128, v131, 0x3c088889
	v_fmaak_f32 v131, v128, v131, 0x3d2aaaab
	v_fmaak_f32 v131, v128, v131, 0x3e2aaaab
	v_fma_f32 v131, v128, v131, 0.5
	v_fma_f32 v131, v128, v131, 1.0
	v_mul_f32_e64 v128, v128, -v131
	v_max_f32_e32 v128, 0, v128
	v_sqrt_f32_e32 v128, v128
	v_exp_f32_e32 v130, v130
	v_mul_f32_e32 v128, v129, v128
	s_waitcnt lgkmcnt(0)
	v_mul_f32_e32 v128, v128, v132
	ds_write_b32 v177, v130 offset:7472
	ds_write_b32 v177, v128 offset:3120
	v_mul_f32_e32 v128, 0x3fb8aa3b, v124
	v_add_f32_e32 v124, v124, v124
	v_exp_f32_e32 v130, v128
	v_fmamk_f32 v128, v124, 0x37d00d01, v198
	v_fmaak_f32 v128, v124, v128, 0x3ab60b61
	v_fmaak_f32 v128, v124, v128, 0x3c088889
	v_fmaak_f32 v128, v124, v128, 0x3d2aaaab
	v_fmaak_f32 v128, v124, v128, 0x3e2aaaab
	v_fma_f32 v128, v124, v128, 0.5
	v_fma_f32 v131, v124, v128, 1.0
	v_mul_f32_e64 v124, v124, -v131
	v_max_f32_e32 v124, 0, v124
	v_sqrt_f32_e32 v124, v124
	v_add_u32_e32 v132, 0x800, v178
	ds_read2_b32 v[128:129], v132 offset0:64 offset1:132
	v_mul_f32_e32 v120, v120, v124
	v_add_f32_e32 v124, v192, v125
	v_mul_f32_e32 v124, 0xbfb8aa3b, v124
	v_exp_f32_e32 v124, v124
	s_waitcnt lgkmcnt(0)
	v_mul_f32_e32 v120, v120, v128
	v_add_f32_e32 v124, 1.0, v124
	v_rcp_f32_e32 v124, v124
	s_nop 0
	v_mul_f32_e32 v124, v221, v124
	v_mul_f32_e32 v125, 0x3fb8aa3b, v124
	v_add_f32_e32 v124, v124, v124
	v_fmamk_f32 v128, v124, 0x37d00d01, v198
	v_fmaak_f32 v128, v124, v128, 0x3ab60b61
	v_fmaak_f32 v128, v124, v128, 0x3c088889
	v_fmaak_f32 v128, v124, v128, 0x3d2aaaab
	v_fmaak_f32 v128, v124, v128, 0x3e2aaaab
	v_fma_f32 v128, v124, v128, 0.5
	v_fma_f32 v128, v124, v128, 1.0
	v_mul_f32_e64 v124, v124, -v128
	v_max_f32_e32 v124, 0, v124
	v_sqrt_f32_e32 v124, v124
	v_exp_f32_e32 v125, v125
	v_add_u32_e32 v128, 0xa00, v178
	v_mul_f32_e32 v121, v121, v124
	v_add_u32_e32 v124, 0x1800, v178
	v_mul_f32_e32 v121, v121, v129
	ds_write2_b32 v124, v130, v125 offset0:128 offset1:196
	ds_write2_b32 v132, v120, v121 offset0:64 offset1:132
	v_add_f32_e32 v120, v192, v126
	v_mul_f32_e32 v120, 0xbfb8aa3b, v120
	v_exp_f32_e32 v120, v120
	v_add_f32_e32 v121, v191, v122
	v_mul_f32_e32 v121, 0xbfb8aa3b, v121
	v_exp_f32_e32 v121, v121
	v_add_f32_e32 v120, 1.0, v120
	v_rcp_f32_e32 v120, v120
	v_add_f32_e32 v121, 1.0, v121
	v_rcp_f32_e32 v122, v121
	v_mul_f32_e32 v120, v221, v120
	v_add_f32_e32 v125, v120, v120
	v_mul_f32_e32 v121, 0x3fb8aa3b, v120
	v_fmamk_f32 v120, v125, 0x37d00d01, v198
	v_fmaak_f32 v120, v125, v120, 0x3ab60b61
	v_fmaak_f32 v120, v125, v120, 0x3c088889
	v_fmaak_f32 v120, v125, v120, 0x3d2aaaab
	v_fmaak_f32 v120, v125, v120, 0x3e2aaaab
	v_fma_f32 v120, v125, v120, 0.5
	v_fma_f32 v126, v125, v120, 1.0
	v_mul_f32_e64 v125, v125, -v126
	v_max_f32_e32 v125, 0, v125
	v_exp_f32_e32 v124, v121
	ds_read2_b32 v[120:121], v128 offset0:72 offset1:140
	v_sqrt_f32_e32 v125, v125
	s_nop 0
	v_mul_f32_e32 v122, v122, v125
	s_waitcnt lgkmcnt(0)
	v_mul_f32_e32 v120, v122, v120
	v_add_f32_e32 v122, v192, v127
	v_mul_f32_e32 v122, 0xbfb8aa3b, v122
	v_exp_f32_e32 v122, v122
	s_nop 0
	v_add_f32_e32 v122, 1.0, v122
	v_rcp_f32_e32 v122, v122
	s_nop 0
	v_mul_f32_e32 v122, v221, v122
	v_mul_f32_e32 v125, 0x3fb8aa3b, v122
	v_add_f32_e32 v122, v122, v122
	v_fmamk_f32 v126, v122, 0x37d00d01, v198
	v_fmaak_f32 v126, v122, v126, 0x3ab60b61
	v_fmaak_f32 v126, v122, v126, 0x3c088889
	v_fmaak_f32 v126, v122, v126, 0x3d2aaaab
	v_fmaak_f32 v126, v122, v126, 0x3e2aaaab
	v_fma_f32 v126, v122, v126, 0.5
	v_fma_f32 v126, v122, v126, 1.0
	v_mul_f32_e64 v122, v122, -v126
	v_max_f32_e32 v122, 0, v122
	v_sqrt_f32_e32 v122, v122
	v_exp_f32_e32 v125, v125
	v_add_u32_e32 v126, 0x1c00, v174
	v_mul_f32_e32 v122, v123, v122
	v_mul_f32_e32 v121, v122, v121
	v_add_u32_e32 v122, 0x1c00, v178
	ds_write2_b32 v122, v124, v125 offset0:8 offset1:76
	ds_write2_b32 v128, v120, v121 offset0:72 offset1:140
	s_waitcnt lgkmcnt(0)
	v_add_u32_e32 v120, 0x1800, v174
	v_add_u32_e32 v122, 0x800, v174
	ds_read2_b32 v[120:121], v120 offset0:128 offset1:196
	ds_read2_b32 v[122:123], v122 offset0:64 offset1:132
	v_add_u32_e32 v124, 0xa00, v174
	ds_read2_b32 v[124:125], v124 offset0:72 offset1:140
	s_waitcnt lgkmcnt(1)
	v_fma_f32 v122, v164, v120, v122
	v_mul_f32_e32 v120, v169, v120
	v_fmac_f32_e32 v123, v122, v121
	v_mul_f32_e32 v122, v120, v121
	ds_read2_b32 v[120:121], v126 offset0:8 offset1:76
	s_waitcnt lgkmcnt(0)
	v_fma_f32 v123, v123, v120, v124
	v_mul_f32_e32 v120, v122, v120
	v_add_u32_e32 v122, 0xc00, v174
	v_fmac_f32_e32 v125, v123, v121
	v_mul_f32_e32 v124, v120, v121
	ds_read2_b32 v[120:121], v126 offset0:144 offset1:212
	ds_read2_b32 v[122:123], v122 offset0:80 offset1:148
	s_waitcnt lgkmcnt(0)
	v_fma_f32 v122, v125, v120, v122
	v_mul_f32_e32 v120, v124, v120
	v_fmac_f32_e32 v123, v122, v121
	v_mul_f32_e32 v121, v120, v121
	v_add_u32_e32 v120, 0x2000, v174
	v_add_u32_e32 v122, 0xe00, v174
	ds_read2_b32 v[124:125], v120 offset0:24 offset1:92
	ds_read2_b32 v[126:127], v122 offset0:88 offset1:156
	s_waitcnt lgkmcnt(1)
	v_mov_b32_e32 v139, v124
	s_waitcnt lgkmcnt(0)
	v_fma_f32 v122, v123, v124, v126
	v_fmac_f32_e32 v127, v122, v125
	ds_read2_b32 v[122:123], v120 offset0:160 offset1:228
	v_add_u32_e32 v120, 0x1000, v174
	ds_read2_b32 v[128:129], v120 offset0:96 offset1:164
	s_waitcnt lgkmcnt(0)
	v_fma_f32 v120, v127, v122, v128
	v_fmac_f32_e32 v129, v120, v123
	v_add_u32_e32 v120, 0x2400, v174
	v_add_u32_e32 v128, 0x1200, v174
	ds_read2_b32 v[126:127], v120 offset0:40 offset1:108
	ds_read2_b32 v[130:131], v128 offset0:104 offset1:172
	s_waitcnt lgkmcnt(1)
	v_mov_b32_e32 v138, v127
	s_waitcnt lgkmcnt(0)
	v_fmac_f32_e32 v130, v129, v126
	ds_read2_b32 v[128:129], v120 offset0:176 offset1:244
	v_add_u32_e32 v120, 0x1400, v174
	ds_read2_b32 v[132:133], v120 offset0:112 offset1:180
	v_add_u32_e32 v120, 0x2800, v174
	ds_read2_b32 v[134:135], v120 offset0:56 offset1:124
	v_add_u32_e32 v120, 0x1600, v174
	ds_read2_b32 v[136:137], v120 offset0:120 offset1:188
	v_mov_b32_e32 v120, v130
	v_pk_mul_f32 v[140:141], v[120:121], v[138:139]
	v_mov_b32_e32 v130, v131
	v_mov_b32_e32 v124, v131
	v_pk_fma_f32 v[120:121], v[120:121], v[138:139], v[130:131]
	v_pk_mul_f32 v[124:125], v[140:141], v[124:125]
	s_waitcnt lgkmcnt(3)
	v_mov_b32_e32 v130, v128
	v_mov_b32_e32 v131, v122
	v_mov_b32_e32 v121, v125
	v_pk_mul_f32 v[124:125], v[124:125], v[130:131]
	s_waitcnt lgkmcnt(2)
	v_mov_b32_e32 v122, v132
	v_pk_fma_f32 v[120:121], v[120:121], v[130:131], v[132:133]
	v_pk_mul_f32 v[122:123], v[124:125], v[122:123]
	v_mov_b32_e32 v130, v133
	v_mov_b32_e32 v121, v123
	v_mov_b32_e32 v122, v129
	v_mov_b32_e32 v123, v126
	v_pk_mul_f32 v[124:125], v[120:121], v[122:123]
	v_mov_b32_e32 v126, v133
	v_pk_fma_f32 v[120:121], v[120:121], v[122:123], v[130:131]
	v_pk_mul_f32 v[122:123], v[124:125], v[126:127]
	s_waitcnt lgkmcnt(1)
	v_mov_b32_e32 v124, v134
	v_mov_b32_e32 v125, v128
	v_mov_b32_e32 v121, v123
	v_pk_mul_f32 v[122:123], v[122:123], v[124:125]
	s_waitcnt lgkmcnt(0)
	v_mov_b32_e32 v128, v136
	v_pk_fma_f32 v[120:121], v[120:121], v[124:125], v[136:137]
	v_pk_mul_f32 v[122:123], v[122:123], v[128:129]
	s_waitcnt lgkmcnt(0)
	s_nop 0
	v_mov_b32_e32 v121, v123
	v_mov_b32_e32 v122, v135
	v_mov_b32_e32 v123, v134
	v_pk_mul_f32 v[124:125], v[120:121], v[122:123]
	v_mov_b32_e32 v134, v137
	v_pk_fma_f32 v[164:165], v[120:121], v[122:123], v[134:135]
	v_pk_mul_f32 v[168:169], v[124:125], v[134:135]
	s_cbranch_scc0 .LBB0_194

.LBB0_274:
	v_add_co_u32_e32 v120, vcc, 0x1200b000, v120
	v_lshl_add_u64 v[122:123], v[190:191], 0, v[166:167]
	s_nop 0
	v_addc_co_u32_e32 v121, vcc, 0, v121, vcc
	global_load_dwordx4 v[124:127], v[122:123], off
	s_add_i32 s20, s20, -1
	global_load_dwordx4 v[120:123], v[120:121], off
	s_waitcnt lgkmcnt(0)
	ds_read_b128 v[240:243], v229 offset:11008
	ds_read_b128 v[244:247], v229 offset:11152
	ds_read_b128 v[248:251], v229 offset:11296
	ds_read_b128 v[148:151], v229 offset:11440
	v_lshl_add_u64 v[180:181], v[180:181], 0, s[62:63]
	v_lshl_add_u64 v[190:191], v[190:191], 0, s[62:63]
	s_cmp_lg_u32 s20, 0
	s_waitcnt lgkmcnt(0)
	v_lshlrev_b32_e32 v132, 16, v240
	v_and_b32_e32 v133, 0xffff0000, v240
	v_lshlrev_b32_e32 v128, 16, v241
	v_and_b32_e32 v129, 0xffff0000, v241
	v_lshlrev_b32_e32 v134, 16, v242
	v_and_b32_e32 v135, 0xffff0000, v242
	v_lshlrev_b32_e32 v130, 16, v243
	v_and_b32_e32 v131, 0xffff0000, v243
	v_pk_fma_f32 v[136:137], v[6:7], v[128:129], v[22:23]
	v_pk_fma_f32 v[138:139], v[2:3], v[130:131], v[18:19]
	v_pk_fma_f32 v[132:133], v[4:5], v[132:133], v[20:21]
	v_pk_fma_f32 v[134:135], v[0:1], v[134:135], v[16:17]
	s_waitcnt lgkmcnt(0)
	v_lshlrev_b32_e32 v140, 16, v244
	v_and_b32_e32 v141, 0xffff0000, v244
	v_lshlrev_b32_e32 v128, 16, v245
	v_and_b32_e32 v129, 0xffff0000, v245
	v_lshlrev_b32_e32 v142, 16, v246
	v_and_b32_e32 v143, 0xffff0000, v246
	v_lshlrev_b32_e32 v130, 16, v247
	v_and_b32_e32 v131, 0xffff0000, v247
	v_pk_fma_f32 v[136:137], v[14:15], v[128:129], v[136:137]
	v_pk_fma_f32 v[138:139], v[10:11], v[130:131], v[138:139]
	v_pk_fma_f32 v[132:133], v[12:13], v[140:141], v[132:133]
	v_pk_fma_f32 v[134:135], v[8:9], v[142:143], v[134:135]
	s_waitcnt lgkmcnt(0)
	v_lshlrev_b32_e32 v140, 16, v248
	v_and_b32_e32 v141, 0xffff0000, v248
	v_lshlrev_b32_e32 v128, 16, v249
	v_and_b32_e32 v129, 0xffff0000, v249
	v_lshlrev_b32_e32 v142, 16, v250
	v_and_b32_e32 v143, 0xffff0000, v250
	v_lshlrev_b32_e32 v130, 16, v251
	v_and_b32_e32 v131, 0xffff0000, v251
	v_pk_fma_f32 v[132:133], v[24:25], v[140:141], v[132:133]
	v_pk_fma_f32 v[136:137], v[26:27], v[128:129], v[136:137]
	v_pk_fma_f32 v[140:141], v[28:29], v[142:143], v[134:135]
	v_pk_fma_f32 v[134:135], v[30:31], v[130:131], v[138:139]
	s_waitcnt lgkmcnt(0)
	v_lshlrev_b32_e32 v138, 16, v148
	v_and_b32_e32 v139, 0xffff0000, v148
	v_lshlrev_b32_e32 v128, 16, v149
	v_and_b32_e32 v129, 0xffff0000, v149
	v_lshlrev_b32_e32 v142, 16, v150
	v_and_b32_e32 v143, 0xffff0000, v150
	v_lshlrev_b32_e32 v144, 16, v151
	v_and_b32_e32 v145, 0xffff0000, v151
	ds_read_b128 v[240:243], v229 offset:12160
	ds_read_b128 v[244:247], v229 offset:12304
	ds_read_b128 v[248:251], v229 offset:12448
	ds_read_b128 v[148:151], v229 offset:12592
	v_pk_fma_f32 v[130:131], v[34:35], v[128:129], v[136:137]
	v_pk_fma_f32 v[128:129], v[32:33], v[138:139], v[132:133]
	v_pk_fma_f32 v[134:135], v[38:39], v[144:145], v[134:135]
	v_pk_fma_f32 v[132:133], v[36:37], v[142:143], v[140:141]
	ds_write_b128 v228, v[128:131] offset:2304
	ds_write_b128 v228, v[132:135] offset:2320
	v_cvt_pk_bf16_f32 v128, v128, v129
	v_cvt_pk_bf16_f32 v129, v130, v131
	v_cvt_pk_bf16_f32 v130, v132, v133
	v_cvt_pk_bf16_f32 v131, v134, v135
	ds_write_b128 v229, v[128:131]
	s_waitcnt lgkmcnt(0)
	v_lshlrev_b32_e32 v132, 16, v240
	v_and_b32_e32 v133, 0xffff0000, v240
	v_lshlrev_b32_e32 v128, 16, v241
	v_and_b32_e32 v129, 0xffff0000, v241
	v_lshlrev_b32_e32 v134, 16, v242
	v_and_b32_e32 v135, 0xffff0000, v242
	v_lshlrev_b32_e32 v130, 16, v243
	v_and_b32_e32 v131, 0xffff0000, v243
	v_pk_fma_f32 v[136:137], v[6:7], v[128:129], v[22:23]
	v_pk_fma_f32 v[138:139], v[2:3], v[130:131], v[18:19]
	v_pk_fma_f32 v[132:133], v[4:5], v[132:133], v[20:21]
	v_pk_fma_f32 v[134:135], v[0:1], v[134:135], v[16:17]
	s_waitcnt lgkmcnt(0)
	v_lshlrev_b32_e32 v140, 16, v244
	v_and_b32_e32 v141, 0xffff0000, v244
	v_lshlrev_b32_e32 v128, 16, v245
	v_and_b32_e32 v129, 0xffff0000, v245
	v_lshlrev_b32_e32 v142, 16, v246
	v_and_b32_e32 v143, 0xffff0000, v246
	v_lshlrev_b32_e32 v130, 16, v247
	v_and_b32_e32 v131, 0xffff0000, v247
	v_pk_fma_f32 v[136:137], v[14:15], v[128:129], v[136:137]
	v_pk_fma_f32 v[138:139], v[10:11], v[130:131], v[138:139]
	v_pk_fma_f32 v[132:133], v[12:13], v[140:141], v[132:133]
	v_pk_fma_f32 v[134:135], v[8:9], v[142:143], v[134:135]
	s_waitcnt lgkmcnt(0)
	v_lshlrev_b32_e32 v140, 16, v248
	v_and_b32_e32 v141, 0xffff0000, v248
	v_lshlrev_b32_e32 v128, 16, v249
	v_and_b32_e32 v129, 0xffff0000, v249
	v_lshlrev_b32_e32 v142, 16, v250
	v_and_b32_e32 v143, 0xffff0000, v250
	v_lshlrev_b32_e32 v130, 16, v251
	v_and_b32_e32 v131, 0xffff0000, v251
	v_pk_fma_f32 v[132:133], v[24:25], v[140:141], v[132:133]
	v_pk_fma_f32 v[136:137], v[26:27], v[128:129], v[136:137]
	v_pk_fma_f32 v[140:141], v[28:29], v[142:143], v[134:135]
	v_pk_fma_f32 v[134:135], v[30:31], v[130:131], v[138:139]
	s_waitcnt lgkmcnt(0)
	v_lshlrev_b32_e32 v138, 16, v148
	v_and_b32_e32 v139, 0xffff0000, v148
	v_lshlrev_b32_e32 v128, 16, v149
	v_and_b32_e32 v129, 0xffff0000, v149
	v_lshlrev_b32_e32 v142, 16, v150
	v_and_b32_e32 v143, 0xffff0000, v150
	v_lshlrev_b32_e32 v144, 16, v151
	v_and_b32_e32 v145, 0xffff0000, v151
	v_pk_fma_f32 v[130:131], v[34:35], v[128:129], v[136:137]
	v_pk_fma_f32 v[128:129], v[32:33], v[138:139], v[132:133]
	v_pk_fma_f32 v[134:135], v[38:39], v[144:145], v[134:135]
	v_pk_fma_f32 v[132:133], v[36:37], v[142:143], v[140:141]
	ds_write_b128 v228, v[128:131] offset:4480
	ds_write_b128 v228, v[132:135] offset:4496
	v_cvt_pk_bf16_f32 v128, v128, v129
	v_cvt_pk_bf16_f32 v129, v130, v131
	v_cvt_pk_bf16_f32 v130, v132, v133
	v_cvt_pk_bf16_f32 v131, v134, v135
	ds_write_b128 v229, v[128:131] offset:1152
	s_waitcnt lgkmcnt(0)
	ds_read_b128 v[128:131], v222
	ds_read_b128 v[240:243], v222 offset:64
	s_waitcnt lgkmcnt(1)
	v_mfma_f32_16x16x32_bf16 v[132:135], v[128:131], v[40:43], 0
	s_waitcnt lgkmcnt(0)
	v_mfma_f32_16x16x32_bf16 v[244:247], v[240:243], v[44:47], v[132:135]
	v_mfma_f32_16x16x32_bf16 v[136:139], v[128:131], v[72:75], 0
	v_mfma_f32_16x16x32_bf16 v[132:135], v[128:131], v[48:51], 0
	s_nop 5
	v_add_f32_e32 v176, v173, v244
	v_mul_f32_e32 v176, 0xbfb8aa3b, v176
	v_exp_f32_e32 v176, v176
	v_mfma_f32_16x16x32_bf16 v[248:251], v[240:243], v[76:79], v[136:139]
	v_add_f32_e32 v176, 1.0, v176
	v_mfma_f32_16x16x32_bf16 v[144:147], v[240:243], v[52:55], v[132:135]
	v_rcp_f32_e32 v176, v176
	s_nop 4
	v_add_f32_e32 v192, v175, v248
	v_mul_f32_e32 v192, 0xbfb8aa3b, v192
	v_mfma_f32_16x16x32_bf16 v[132:135], v[128:131], v[56:59], 0
	v_exp_f32_e32 v192, v192
	v_mul_f32_e32 v176, v236, v176
	v_add_f32_e32 v144, v230, v144
	v_mfma_f32_16x16x32_bf16 v[136:139], v[128:131], v[80:83], 0
	v_add_f32_e32 v192, 1.0, v192
	v_mul_f32_e32 v144, 0xbfb8aa3b, v144
	v_exp_f32_e32 v144, v144
	v_mfma_f32_16x16x32_bf16 v[140:143], v[240:243], v[60:63], v[132:135]
	v_add_f32_e32 v146, v230, v146
	v_mul_f32_e32 v146, 0xbfb8aa3b, v146
	v_add_f32_e32 v144, 1.0, v144
	v_mfma_f32_16x16x32_bf16 v[132:135], v[128:131], v[64:67], 0
	v_rcp_f32_e32 v144, v144
	v_exp_f32_e32 v146, v146
	s_nop 1
	v_add_f32_e32 v140, v232, v140
	v_mfma_f32_16x16x32_bf16 v[148:151], v[240:243], v[84:87], v[136:139]
	v_mul_f32_e32 v144, v237, v144
	v_add_f32_e32 v146, 1.0, v146
	v_rcp_f32_e32 v146, v146
	v_mfma_f32_16x16x32_bf16 v[136:139], v[128:131], v[88:91], 0
	v_mul_f32_e32 v140, 0xbfb8aa3b, v140
	s_nop 2
	v_add_f32_e32 v148, v231, v148
	v_mul_f32_e32 v148, 0xbfb8aa3b, v148
	v_mfma_f32_16x16x32_bf16 v[128:131], v[128:131], v[100:103], 0
	v_exp_f32_e32 v148, v148
	v_mul_f32_e32 v146, v237, v146
	v_exp_f32_e32 v140, v140
	v_mfma_f32_16x16x32_bf16 v[132:135], v[240:243], v[68:71], v[132:135]
	v_add_f32_e32 v148, 1.0, v148
	v_rcp_f32_e32 v148, v148
	v_add_f32_e32 v140, 1.0, v140
	v_mfma_f32_16x16x32_bf16 v[136:139], v[240:243], v[92:95], v[136:139]
	v_rcp_f32_e32 v140, v140
	s_nop 2
	v_add_f32_e32 v132, v235, v132
	v_mul_f32_e32 v132, 0xbfb8aa3b, v132
	v_mfma_f32_16x16x32_bf16 v[128:131], v[240:243], v[104:107], v[128:131]
	v_rcp_f32_e32 v240, v192
	v_mul_f32_e32 v192, 0x3fb8aa3b, v176
	v_add_f32_e32 v176, v176, v176
	v_exp_f32_e32 v241, v192
	v_fmamk_f32 v192, v176, 0x37d00d01, v198
	v_fmaak_f32 v192, v176, v192, 0x3ab60b61
	v_fmaak_f32 v192, v176, v192, 0x3c088889
	v_fmaak_f32 v192, v176, v192, 0x3d2aaaab
	v_fmaak_f32 v192, v176, v192, 0x3e2aaaab
	v_fma_f32 v192, v176, v192, 0.5
	v_fma_f32 v242, v176, v192, 1.0
	v_mul_f32_e64 v176, v176, -v242
	v_add_u32_e32 v243, 0x800, v223
	v_max_f32_e32 v176, 0, v176
	ds_read2_b32 v[192:193], v243 offset0:64 offset1:80
	v_sqrt_f32_e32 v176, v176
	v_mul_f32_e32 v140, v238, v140
	v_add_f32_e32 v136, v233, v136
	v_mul_f32_e32 v136, 0xbfb8aa3b, v136
	v_mul_f32_e32 v176, v240, v176
	s_waitcnt lgkmcnt(0)
	v_mul_f32_e32 v176, v192, v176
	ds_write_b32 v223, v241 offset:6656
	ds_write_b32 v223, v176 offset:2304
	v_add_f32_e32 v176, v173, v245
	v_mul_f32_e32 v176, 0xbfb8aa3b, v176
	v_exp_f32_e32 v176, v176
	v_add_f32_e32 v192, v175, v249
	v_mul_f32_e32 v192, 0xbfb8aa3b, v192
	v_exp_f32_e32 v192, v192
	v_add_f32_e32 v176, 1.0, v176
	v_rcp_f32_e32 v176, v176
	v_exp_f32_e32 v136, v136
	v_add_f32_e32 v192, 1.0, v192
	v_rcp_f32_e32 v192, v192
	v_mul_f32_e32 v176, v236, v176
	v_mul_f32_e32 v240, 0x3fb8aa3b, v176
	v_add_f32_e32 v176, v176, v176
	v_exp_f32_e32 v242, v240
	v_fmamk_f32 v240, v176, 0x37d00d01, v198
	v_fmaak_f32 v240, v176, v240, 0x3ab60b61
	v_fmaak_f32 v240, v176, v240, 0x3c088889
	v_fmaak_f32 v240, v176, v240, 0x3d2aaaab
	v_fmaak_f32 v240, v176, v240, 0x3e2aaaab
	v_fma_f32 v240, v176, v240, 0.5
	v_fma_f32 v244, v176, v240, 1.0
	v_mul_f32_e64 v176, v176, -v244
	v_max_f32_e32 v176, 0, v176
	v_sqrt_f32_e32 v176, v176
	ds_read2_b32 v[240:241], v243 offset0:132 offset1:200
	v_add_f32_e32 v136, 1.0, v136
	v_rcp_f32_e32 v136, v136
	v_mul_f32_e32 v176, v192, v176
	v_add_f32_e32 v192, v173, v246
	v_mul_f32_e32 v192, 0xbfb8aa3b, v192
	v_exp_f32_e32 v192, v192
	s_waitcnt lgkmcnt(0)
	v_mul_f32_e32 v176, v240, v176
	v_add_f32_e32 v240, v175, v250
	v_mul_f32_e32 v240, 0xbfb8aa3b, v240
	v_add_f32_e32 v192, 1.0, v192
	v_rcp_f32_e32 v192, v192
	v_exp_f32_e32 v240, v240
	v_add_f32_e32 v137, v233, v137
	v_mul_f32_e32 v137, 0xbfb8aa3b, v137
	v_mul_f32_e32 v192, v236, v192
	v_mul_f32_e32 v244, 0x3fb8aa3b, v192
	v_add_f32_e32 v192, v192, v192
	v_fmamk_f32 v245, v192, 0x37d00d01, v198
	v_fmaak_f32 v245, v192, v245, 0x3ab60b61
	v_fmaak_f32 v245, v192, v245, 0x3c088889
	v_fmaak_f32 v245, v192, v245, 0x3d2aaaab
	v_fmaak_f32 v245, v192, v245, 0x3e2aaaab
	v_fma_f32 v245, v192, v245, 0.5
	v_fma_f32 v245, v192, v245, 1.0
	v_mul_f32_e64 v192, v192, -v245
	v_add_f32_e32 v240, 1.0, v240
	v_max_f32_e32 v192, 0, v192
	v_rcp_f32_e32 v240, v240
	v_sqrt_f32_e32 v192, v192
	v_exp_f32_e32 v244, v244
	v_exp_f32_e32 v137, v137
	v_add_f32_e32 v138, v233, v138
	v_mul_f32_e32 v192, v240, v192
	v_add_u32_e32 v240, 0x1a00, v223
	v_mul_f32_e32 v192, v241, v192
	ds_write2_b32 v240, v242, v244 offset0:68 offset1:136
	ds_write2_b32 v243, v176, v192 offset0:132 offset1:200
	v_add_f32_e32 v176, v173, v247
	v_mul_f32_e32 v176, 0xbfb8aa3b, v176
	v_exp_f32_e32 v176, v176
	v_add_f32_e32 v192, v175, v251
	v_mul_f32_e32 v192, 0xbfb8aa3b, v192
	v_exp_f32_e32 v192, v192
	v_add_f32_e32 v176, 1.0, v176
	v_rcp_f32_e32 v176, v176
	ds_read_b32 v242, v223 offset:3120
	v_add_f32_e32 v192, 1.0, v192
	v_rcp_f32_e32 v192, v192
	v_mul_f32_e32 v176, v236, v176
	v_mul_f32_e32 v240, 0x3fb8aa3b, v176
	v_add_f32_e32 v176, v176, v176
	v_fmamk_f32 v241, v176, 0x37d00d01, v198
	v_fmaak_f32 v241, v176, v241, 0x3ab60b61
	v_fmaak_f32 v241, v176, v241, 0x3c088889
	v_fmaak_f32 v241, v176, v241, 0x3d2aaaab
	v_fmaak_f32 v241, v176, v241, 0x3e2aaaab
	v_fma_f32 v241, v176, v241, 0.5
	v_fma_f32 v241, v176, v241, 1.0
	v_mul_f32_e64 v176, v176, -v241
	v_max_f32_e32 v176, 0, v176
	v_sqrt_f32_e32 v176, v176
	v_exp_f32_e32 v240, v240
	v_add_f32_e32 v137, 1.0, v137
	v_mul_f32_e32 v138, 0xbfb8aa3b, v138
	v_mul_f32_e32 v176, v192, v176
	s_waitcnt lgkmcnt(0)
	v_mul_f32_e32 v176, v242, v176
	ds_write_b32 v223, v240 offset:7472
	ds_write_b32 v223, v176 offset:3120
	v_mul_f32_e32 v176, 0x3fb8aa3b, v144
	v_add_f32_e32 v144, v144, v144
	v_fmamk_f32 v192, v144, 0x37d00d01, v198
	v_fmaak_f32 v192, v144, v192, 0x3ab60b61
	v_fmaak_f32 v192, v144, v192, 0x3c088889
	v_fmaak_f32 v192, v144, v192, 0x3d2aaaab
	v_fmaak_f32 v192, v144, v192, 0x3e2aaaab
	v_fma_f32 v192, v144, v192, 0.5
	v_fma_f32 v192, v144, v192, 1.0
	v_mul_f32_e64 v144, v144, -v192
	v_max_f32_e32 v144, 0, v144
	v_sqrt_f32_e32 v144, v144
	v_exp_f32_e32 v176, v176
	v_exp_f32_e32 v138, v138
	v_exp_f32_e32 v132, v132
	v_mul_f32_e32 v144, v148, v144
	v_mul_f32_e32 v144, v193, v144
	ds_write_b32 v223, v176 offset:6720
	ds_write_b32 v223, v144 offset:2368
	v_add_f32_e32 v144, v230, v145
	v_mul_f32_e32 v144, 0xbfb8aa3b, v144
	v_exp_f32_e32 v144, v144
	v_add_f32_e32 v145, v231, v149
	v_mul_f32_e32 v145, 0xbfb8aa3b, v145
	v_exp_f32_e32 v145, v145
	v_add_f32_e32 v144, 1.0, v144
	v_rcp_f32_e32 v144, v144
	v_add_u32_e32 v193, 0x800, v224
	v_add_f32_e32 v145, 1.0, v145
	v_rcp_f32_e32 v148, v145
	v_mul_f32_e32 v144, v237, v144
	v_add_f32_e32 v176, v144, v144
	v_mul_f32_e32 v145, 0x3fb8aa3b, v144
	v_fmamk_f32 v144, v176, 0x37d00d01, v198
	v_fmaak_f32 v144, v176, v144, 0x3ab60b61
	v_fmaak_f32 v144, v176, v144, 0x3c088889
	v_fmaak_f32 v144, v176, v144, 0x3d2aaaab
	v_fmaak_f32 v144, v176, v144, 0x3e2aaaab
	v_fma_f32 v144, v176, v144, 0.5
	v_fma_f32 v192, v176, v144, 1.0
	v_mul_f32_e64 v176, v176, -v192
	v_max_f32_e32 v176, 0, v176
	v_exp_f32_e32 v149, v145
	ds_read2_b32 v[144:145], v193 offset0:132 offset1:200
	v_sqrt_f32_e32 v176, v176
	v_add_f32_e32 v138, 1.0, v138
	v_rcp_f32_e32 v138, v138
	v_add_f32_e32 v132, 1.0, v132
	v_mul_f32_e32 v148, v148, v176
	s_waitcnt lgkmcnt(0)
	v_mul_f32_e32 v144, v148, v144
	v_add_f32_e32 v148, v231, v150
	v_mul_f32_e32 v150, 0x3fb8aa3b, v146
	v_add_f32_e32 v146, v146, v146
	v_fmamk_f32 v176, v146, 0x37d00d01, v198
	v_fmaak_f32 v176, v146, v176, 0x3ab60b61
	v_fmaak_f32 v176, v146, v176, 0x3c088889
	v_mul_f32_e32 v148, 0xbfb8aa3b, v148
	v_fmaak_f32 v176, v146, v176, 0x3d2aaaab
	v_exp_f32_e32 v148, v148
	v_fmaak_f32 v176, v146, v176, 0x3e2aaaab
	v_fma_f32 v176, v146, v176, 0.5
	v_fma_f32 v176, v146, v176, 1.0
	v_mul_f32_e64 v146, v146, -v176
	v_add_f32_e32 v148, 1.0, v148
	v_max_f32_e32 v146, 0, v146
	v_rcp_f32_e32 v148, v148
	v_sqrt_f32_e32 v146, v146
	v_exp_f32_e32 v150, v150
	v_rcp_f32_e32 v132, v132
	v_add_f32_e32 v128, v234, v128
	v_mul_f32_e32 v146, v148, v146
	v_mul_f32_e32 v145, v146, v145
	v_add_u32_e32 v146, 0x1a00, v224
	ds_write2_b32 v146, v149, v150 offset0:68 offset1:136
	ds_write2_b32 v193, v144, v145 offset0:132 offset1:200
	v_add_f32_e32 v144, v230, v147
	v_mul_f32_e32 v144, 0xbfb8aa3b, v144
	v_exp_f32_e32 v144, v144
	ds_read_b32 v148, v224 offset:3120
	v_mul_f32_e32 v132, v239, v132
	v_mul_f32_e32 v128, 0xbfb8aa3b, v128
	v_add_f32_e32 v144, 1.0, v144
	v_rcp_f32_e32 v145, v144
	v_add_f32_e32 v144, v231, v151
	v_mul_f32_e32 v144, 0xbfb8aa3b, v144
	v_exp_f32_e32 v144, v144
	v_mul_f32_e32 v146, v237, v145
	v_mul_f32_e32 v145, 0x3fb8aa3b, v146
	v_add_f32_e32 v146, v146, v146
	v_fmamk_f32 v147, v146, 0x37d00d01, v198
	v_fmaak_f32 v147, v146, v147, 0x3ab60b61
	v_fmaak_f32 v147, v146, v147, 0x3c088889
	v_fmaak_f32 v147, v146, v147, 0x3d2aaaab
	v_fmaak_f32 v147, v146, v147, 0x3e2aaaab
	v_fma_f32 v147, v146, v147, 0.5
	v_fma_f32 v147, v146, v147, 1.0
	v_mul_f32_e64 v146, v146, -v147
	v_add_f32_e32 v144, 1.0, v144
	v_max_f32_e32 v146, 0, v146
	v_rcp_f32_e32 v144, v144
	v_sqrt_f32_e32 v146, v146
	v_exp_f32_e32 v145, v145
	v_exp_f32_e32 v128, v128
	v_add_f32_e32 v129, v234, v129
	v_mul_f32_e32 v144, v144, v146
	s_waitcnt lgkmcnt(0)
	v_mul_f32_e32 v144, v144, v148
	ds_write_b32 v224, v145 offset:7472
	ds_write_b32 v224, v144 offset:3120
	v_mul_f32_e32 v144, 0x3fb8aa3b, v140
	v_add_f32_e32 v140, v140, v140
	v_fmamk_f32 v145, v140, 0x37d00d01, v198
	v_fmaak_f32 v145, v140, v145, 0x3ab60b61
	v_fmaak_f32 v145, v140, v145, 0x3c088889
	v_fmaak_f32 v145, v140, v145, 0x3d2aaaab
	v_fmaak_f32 v145, v140, v145, 0x3e2aaaab
	v_fma_f32 v145, v140, v145, 0.5
	v_fma_f32 v145, v140, v145, 1.0
	v_mul_f32_e64 v140, v140, -v145
	v_max_f32_e32 v140, 0, v140
	ds_read_b32 v146, v223 offset:2432
	v_sqrt_f32_e32 v140, v140
	v_exp_f32_e32 v144, v144
	v_add_f32_e32 v128, 1.0, v128
	v_rcp_f32_e32 v128, v128
	v_mul_f32_e32 v136, v136, v140
	s_waitcnt lgkmcnt(0)
	v_mul_f32_e32 v136, v136, v146
	ds_write_b32 v223, v144 offset:6784
	ds_write_b32 v223, v136 offset:2432
	v_add_f32_e32 v136, v232, v141
	v_mul_f32_e32 v136, 0xbfb8aa3b, v136
	v_exp_f32_e32 v136, v136
	v_rcp_f32_e32 v140, v137
	v_add_u32_e32 v146, 0x800, v225
	v_mul_f32_e32 v129, 0xbfb8aa3b, v129
	v_add_f32_e32 v136, 1.0, v136
	v_rcp_f32_e32 v136, v136
	v_exp_f32_e32 v129, v129
	v_add_f32_e32 v131, v234, v131
	v_mul_f32_e32 v131, 0xbfb8aa3b, v131
	v_mul_f32_e32 v136, v238, v136
	v_add_f32_e32 v144, v136, v136
	v_mul_f32_e32 v137, 0x3fb8aa3b, v136
	v_fmamk_f32 v136, v144, 0x37d00d01, v198
	v_fmaak_f32 v136, v144, v136, 0x3ab60b61
	v_fmaak_f32 v136, v144, v136, 0x3c088889
	v_fmaak_f32 v136, v144, v136, 0x3d2aaaab
	v_fmaak_f32 v136, v144, v136, 0x3e2aaaab
	v_fma_f32 v136, v144, v136, 0.5
	v_fma_f32 v145, v144, v136, 1.0
	v_mul_f32_e64 v144, v144, -v145
	v_max_f32_e32 v144, 0, v144
	v_exp_f32_e32 v141, v137
	ds_read2_b32 v[136:137], v146 offset0:132 offset1:200
	v_sqrt_f32_e32 v144, v144
	v_add_f32_e32 v129, 1.0, v129
	v_rcp_f32_e32 v129, v129
	v_exp_f32_e32 v131, v131
	v_mul_f32_e32 v140, v140, v144
	s_waitcnt lgkmcnt(0)
	v_mul_f32_e32 v136, v140, v136
	v_add_f32_e32 v140, v232, v142
	v_mul_f32_e32 v140, 0xbfb8aa3b, v140
	v_exp_f32_e32 v140, v140
	v_add_f32_e32 v131, 1.0, v131
	v_rcp_f32_e32 v131, v131
	v_add_f32_e32 v140, 1.0, v140
	v_rcp_f32_e32 v140, v140
	s_nop 0
	v_mul_f32_e32 v140, v238, v140
	v_mul_f32_e32 v142, 0x3fb8aa3b, v140
	v_add_f32_e32 v140, v140, v140
	v_fmamk_f32 v144, v140, 0x37d00d01, v198
	v_fmaak_f32 v144, v140, v144, 0x3ab60b61
	v_fmaak_f32 v144, v140, v144, 0x3c088889
	v_fmaak_f32 v144, v140, v144, 0x3d2aaaab
	v_fmaak_f32 v144, v140, v144, 0x3e2aaaab
	v_fma_f32 v144, v140, v144, 0.5
	v_fma_f32 v144, v140, v144, 1.0
	v_mul_f32_e64 v140, v140, -v144
	v_max_f32_e32 v140, 0, v140
	v_sqrt_f32_e32 v140, v140
	v_exp_f32_e32 v142, v142
	v_mul_f32_e32 v138, v138, v140
	v_mul_f32_e32 v137, v138, v137
	v_add_u32_e32 v138, 0x1a00, v225
	ds_write2_b32 v138, v141, v142 offset0:68 offset1:136
	ds_write2_b32 v146, v136, v137 offset0:132 offset1:200
	v_add_f32_e32 v136, v232, v143
	v_mul_f32_e32 v136, 0xbfb8aa3b, v136
	v_exp_f32_e32 v136, v136
	v_add_f32_e32 v137, v233, v139
	v_mul_f32_e32 v137, 0xbfb8aa3b, v137
	v_exp_f32_e32 v137, v137
	v_add_f32_e32 v136, 1.0, v136
	v_rcp_f32_e32 v136, v136
	ds_read_b32 v140, v225 offset:3120
	v_add_f32_e32 v137, 1.0, v137
	v_rcp_f32_e32 v137, v137
	v_mul_f32_e32 v136, v238, v136
	v_mul_f32_e32 v138, 0x3fb8aa3b, v136
	v_add_f32_e32 v136, v136, v136
	v_fmamk_f32 v139, v136, 0x37d00d01, v198
	v_fmaak_f32 v139, v136, v139, 0x3ab60b61
	v_fmaak_f32 v139, v136, v139, 0x3c088889
	v_fmaak_f32 v139, v136, v139, 0x3d2aaaab
	v_fmaak_f32 v139, v136, v139, 0x3e2aaaab
	v_fma_f32 v139, v136, v139, 0.5
	v_fma_f32 v139, v136, v139, 1.0
	v_mul_f32_e64 v136, v136, -v139
	v_max_f32_e32 v136, 0, v136
	v_sqrt_f32_e32 v136, v136
	v_exp_f32_e32 v138, v138
	v_mul_f32_e32 v136, v137, v136
	s_waitcnt lgkmcnt(0)
	v_mul_f32_e32 v136, v136, v140
	ds_write_b32 v225, v138 offset:7472
	ds_write_b32 v225, v136 offset:3120
	v_mul_f32_e32 v136, 0x3fb8aa3b, v132
	v_add_f32_e32 v132, v132, v132
	v_exp_f32_e32 v138, v136
	v_fmamk_f32 v136, v132, 0x37d00d01, v198
	v_fmaak_f32 v136, v132, v136, 0x3ab60b61
	v_fmaak_f32 v136, v132, v136, 0x3c088889
	v_fmaak_f32 v136, v132, v136, 0x3d2aaaab
	v_fmaak_f32 v136, v132, v136, 0x3e2aaaab
	v_fma_f32 v136, v132, v136, 0.5
	v_fma_f32 v139, v132, v136, 1.0
	v_mul_f32_e64 v132, v132, -v139
	v_max_f32_e32 v132, 0, v132
	v_sqrt_f32_e32 v132, v132
	v_add_u32_e32 v140, 0x800, v226
	ds_read2_b32 v[136:137], v140 offset0:64 offset1:132
	s_waitcnt vmcnt(1)
	v_lshlrev_b32_e32 v139, 16, v127
	v_mul_f32_e32 v128, v128, v132
	v_add_f32_e32 v132, v235, v133
	v_mul_f32_e32 v132, 0xbfb8aa3b, v132
	v_exp_f32_e32 v132, v132
	s_waitcnt lgkmcnt(0)
	v_mul_f32_e32 v128, v128, v136
	v_and_b32_e32 v127, 0xffff0000, v127
	v_add_f32_e32 v132, 1.0, v132
	v_rcp_f32_e32 v132, v132
	s_nop 0
	v_mul_f32_e32 v132, v239, v132
	v_mul_f32_e32 v133, 0x3fb8aa3b, v132
	v_add_f32_e32 v132, v132, v132
	v_fmamk_f32 v136, v132, 0x37d00d01, v198
	v_fmaak_f32 v136, v132, v136, 0x3ab60b61
	v_fmaak_f32 v136, v132, v136, 0x3c088889
	v_fmaak_f32 v136, v132, v136, 0x3d2aaaab
	v_fmaak_f32 v136, v132, v136, 0x3e2aaaab
	v_fma_f32 v136, v132, v136, 0.5
	v_fma_f32 v136, v132, v136, 1.0
	v_mul_f32_e64 v132, v132, -v136
	v_max_f32_e32 v132, 0, v132
	v_sqrt_f32_e32 v132, v132
	v_exp_f32_e32 v133, v133
	v_add_u32_e32 v136, 0xa00, v226
	v_mul_f32_e32 v129, v129, v132
	v_add_u32_e32 v132, 0x1800, v226
	v_mul_f32_e32 v129, v129, v137
	ds_write2_b32 v132, v138, v133 offset0:128 offset1:196
	ds_write2_b32 v140, v128, v129 offset0:64 offset1:132
	v_add_f32_e32 v128, v235, v134
	v_mul_f32_e32 v128, 0xbfb8aa3b, v128
	v_exp_f32_e32 v128, v128
	v_add_f32_e32 v129, v234, v130
	v_mul_f32_e32 v129, 0xbfb8aa3b, v129
	v_exp_f32_e32 v129, v129
	v_add_f32_e32 v128, 1.0, v128
	v_rcp_f32_e32 v128, v128
	v_lshlrev_b32_e32 v137, 16, v125
	v_add_f32_e32 v129, 1.0, v129
	v_rcp_f32_e32 v130, v129
	v_mul_f32_e32 v128, v239, v128
	v_add_f32_e32 v133, v128, v128
	v_mul_f32_e32 v129, 0x3fb8aa3b, v128
	v_fmamk_f32 v128, v133, 0x37d00d01, v198
	v_fmaak_f32 v128, v133, v128, 0x3ab60b61
	v_fmaak_f32 v128, v133, v128, 0x3c088889
	v_fmaak_f32 v128, v133, v128, 0x3d2aaaab
	v_fmaak_f32 v128, v133, v128, 0x3e2aaaab
	v_fma_f32 v128, v133, v128, 0.5
	v_fma_f32 v134, v133, v128, 1.0
	v_mul_f32_e64 v133, v133, -v134
	v_max_f32_e32 v133, 0, v133
	v_exp_f32_e32 v132, v129
	ds_read2_b32 v[128:129], v136 offset0:72 offset1:140
	v_sqrt_f32_e32 v133, v133
	v_and_b32_e32 v125, 0xffff0000, v125
	v_lshlrev_b32_e32 v138, 16, v126
	v_and_b32_e32 v126, 0xffff0000, v126
	v_mul_f32_e32 v130, v130, v133
	s_waitcnt lgkmcnt(0)
	v_mul_f32_e32 v128, v130, v128
	v_add_f32_e32 v130, v235, v135
	v_mul_f32_e32 v130, 0xbfb8aa3b, v130
	v_exp_f32_e32 v130, v130
	s_nop 0
	v_add_f32_e32 v130, 1.0, v130
	v_rcp_f32_e32 v130, v130
	s_nop 0
	v_mul_f32_e32 v130, v239, v130
	v_mul_f32_e32 v133, 0x3fb8aa3b, v130
	v_add_f32_e32 v130, v130, v130
	v_fmamk_f32 v134, v130, 0x37d00d01, v198
	v_fmaak_f32 v134, v130, v134, 0x3ab60b61
	v_fmaak_f32 v134, v130, v134, 0x3c088889
	v_fmaak_f32 v134, v130, v134, 0x3d2aaaab
	v_fmaak_f32 v134, v130, v134, 0x3e2aaaab
	v_fma_f32 v134, v130, v134, 0.5
	v_fma_f32 v134, v130, v134, 1.0
	v_mul_f32_e64 v130, v130, -v134
	v_max_f32_e32 v130, 0, v130
	v_sqrt_f32_e32 v130, v130
	v_exp_f32_e32 v133, v133
	v_add_u32_e32 v134, 0xa00, v227
	v_mul_f32_e32 v130, v131, v130
	v_mul_f32_e32 v129, v130, v129
	v_add_u32_e32 v130, 0x1c00, v226
	ds_write2_b32 v130, v132, v133 offset0:8 offset1:76
	ds_write2_b32 v136, v128, v129 offset0:72 offset1:140
	s_waitcnt lgkmcnt(0)
	v_add_u32_e32 v128, 0x1800, v227
	v_add_u32_e32 v132, 0x800, v227
	ds_read2_b32 v[128:129], v128 offset0:128 offset1:196
	ds_read2_b32 v[130:131], v132 offset0:64 offset1:132
	v_lshlrev_b32_e32 v136, 16, v124
	v_mul_f32_e32 v140, 0x3d372713, v136
	v_mul_f32_e32 v140, v140, v136
	v_and_b32_e32 v124, 0xffff0000, v124
	s_waitcnt lgkmcnt(0)
	v_fma_f32 v128, v177, v128, v130
	v_fmac_f32_e32 v131, v128, v129
	v_add_u32_e32 v130, 0x1c00, v227
	ds_write2_b32 v132, v128, v131 offset0:64 offset1:132
	ds_read2_b32 v[128:129], v130 offset0:8 offset1:76
	ds_read2_b32 v[132:133], v134 offset0:72 offset1:140
	s_waitcnt lgkmcnt(0)
	v_fma_f32 v128, v131, v128, v132
	v_fmac_f32_e32 v133, v128, v129
	v_add_u32_e32 v132, 0xc00, v227
	ds_write2_b32 v134, v128, v133 offset0:72 offset1:140
	ds_read2_b32 v[128:129], v130 offset0:144 offset1:212
	ds_read2_b32 v[130:131], v132 offset0:80 offset1:148
	v_add_u32_e32 v134, 0xe00, v227
	s_waitcnt lgkmcnt(0)
	v_fma_f32 v128, v133, v128, v130
	v_fmac_f32_e32 v131, v128, v129
	v_add_u32_e32 v130, 0x2000, v227
	ds_write2_b32 v132, v128, v131 offset0:80 offset1:148
	ds_read2_b32 v[128:129], v130 offset0:24 offset1:92
	ds_read2_b32 v[132:133], v134 offset0:88 offset1:156
	s_waitcnt lgkmcnt(0)
	v_fma_f32 v128, v131, v128, v132
	v_fmac_f32_e32 v133, v128, v129
	v_add_u32_e32 v132, 0x1000, v227
	ds_write2_b32 v134, v128, v133 offset0:88 offset1:156
	ds_read2_b32 v[128:129], v130 offset0:160 offset1:228
	ds_read2_b32 v[130:131], v132 offset0:96 offset1:164
	v_add_u32_e32 v134, 0x1200, v227
	s_waitcnt lgkmcnt(0)
	v_fma_f32 v128, v133, v128, v130
	v_fmac_f32_e32 v131, v128, v129
	v_add_u32_e32 v130, 0x2400, v227
	ds_write2_b32 v132, v128, v131 offset0:96 offset1:164
	ds_read2_b32 v[128:129], v130 offset0:40 offset1:108
	ds_read2_b32 v[132:133], v134 offset0:104 offset1:172
	s_waitcnt lgkmcnt(0)
	v_fma_f32 v128, v131, v128, v132
	v_fmac_f32_e32 v133, v128, v129
	v_add_u32_e32 v132, 0x1400, v227
	ds_write2_b32 v134, v128, v133 offset0:104 offset1:172
	ds_read2_b32 v[128:129], v130 offset0:176 offset1:244
	ds_read2_b32 v[130:131], v132 offset0:112 offset1:180
	s_waitcnt lgkmcnt(0)
	v_fma_f32 v128, v133, v128, v130
	v_fmac_f32_e32 v131, v128, v129
	ds_write2_b32 v132, v128, v131 offset0:112 offset1:180
	v_add_u32_e32 v128, 0x2800, v227
	v_add_u32_e32 v130, 0x1600, v227
	ds_read2_b32 v[128:129], v128 offset0:56 offset1:124
	ds_read2_b32 v[176:177], v130 offset0:120 offset1:188
	s_waitcnt lgkmcnt(0)
	v_fma_f32 v128, v131, v128, v176
	v_fmac_f32_e32 v177, v128, v129
	ds_write2_b32 v130, v128, v177 offset0:120 offset1:188
	s_waitcnt lgkmcnt(0)
	ds_read_b128 v[128:131], v228 offset:2304
	ds_read_b128 v[132:135], v228 offset:2320
	s_waitcnt lgkmcnt(1)
	v_mul_f32_e32 v128, v128, v136
	v_fmac_f32_e32 v136, v140, v136
	v_mul_f32_e32 v136, 0x3fcc422a, v136
	v_mul_f32_e32 v136, 0xbfb8aa3b, v136
	v_exp_f32_e32 v136, v136
	v_mul_f32_e32 v129, v129, v124
	v_add_f32_e32 v136, 1.0, v136
	v_rcp_f32_e32 v136, v136
	s_nop 0
	v_mul_f32_e32 v128, v136, v128
	v_mul_f32_e32 v136, 0x3d372713, v124
	v_mul_f32_e32 v136, v136, v124
	v_fmac_f32_e32 v124, v136, v124
	v_mul_f32_e32 v124, 0x3fcc422a, v124
	v_mul_f32_e32 v124, 0xbfb8aa3b, v124
	v_exp_f32_e32 v124, v124
	s_nop 0
	v_add_f32_e32 v124, 1.0, v124
	v_rcp_f32_e32 v124, v124
	s_nop 0
	v_mul_f32_e32 v124, v124, v129
	v_mul_f32_e32 v129, v130, v137
	v_mul_f32_e32 v130, 0x3d372713, v137
	v_mul_f32_e32 v130, v130, v137
	v_fmac_f32_e32 v137, v130, v137
	v_mul_f32_e32 v130, 0x3fcc422a, v137
	v_mul_f32_e32 v130, 0xbfb8aa3b, v130
	v_exp_f32_e32 v130, v130
	v_cvt_pk_bf16_f32 v124, v128, v124
	s_nop 0
	v_add_f32_e32 v130, 1.0, v130
	v_rcp_f32_e32 v130, v130
	s_nop 0
	v_mul_f32_e32 v129, v130, v129
	v_mul_f32_e32 v130, v131, v125
	v_mul_f32_e32 v131, 0x3d372713, v125
	v_mul_f32_e32 v131, v131, v125
	v_fmac_f32_e32 v125, v131, v125
	v_mul_f32_e32 v125, 0x3fcc422a, v125
	v_mul_f32_e32 v125, 0xbfb8aa3b, v125
	v_exp_f32_e32 v125, v125
	v_mul_f32_e32 v131, 0x3d372713, v138
	v_mul_f32_e32 v131, v131, v138
	v_add_f32_e32 v125, 1.0, v125
	v_rcp_f32_e32 v125, v125
	s_nop 0
	v_mul_f32_e32 v125, v125, v130
	s_waitcnt lgkmcnt(0)
	v_mul_f32_e32 v130, v132, v138
	v_fmac_f32_e32 v138, v131, v138
	v_mul_f32_e32 v131, 0x3fcc422a, v138
	v_mul_f32_e32 v131, 0xbfb8aa3b, v131
	v_exp_f32_e32 v131, v131
	v_mul_f32_e32 v132, 0x3d372713, v126
	v_mul_f32_e32 v132, v132, v126
	v_cvt_pk_bf16_f32 v125, v129, v125
	v_add_f32_e32 v131, 1.0, v131
	v_rcp_f32_e32 v131, v131
	v_lshl_add_u64 v[128:129], v[188:189], 0, v[166:167]
	v_lshl_add_u64 v[188:189], v[188:189], 0, s[60:61]
	v_mul_f32_e32 v130, v131, v130
	v_mul_f32_e32 v131, v133, v126
	v_fmac_f32_e32 v126, v132, v126
	v_mul_f32_e32 v126, 0x3fcc422a, v126
	v_mul_f32_e32 v126, 0xbfb8aa3b, v126
	v_exp_f32_e32 v126, v126
	v_mul_f32_e32 v132, 0x3d372713, v139
	v_mul_f32_e32 v132, v132, v139
	v_mul_f32_e32 v133, 0x3d372713, v127
	v_add_f32_e32 v126, 1.0, v126
	v_rcp_f32_e32 v126, v126
	v_mul_f32_e32 v133, v133, v127
	v_mul_f32_e32 v126, v126, v131
	v_mul_f32_e32 v131, v134, v139
	v_fmac_f32_e32 v139, v132, v139
	v_mul_f32_e32 v132, 0x3fcc422a, v139
	v_mul_f32_e32 v132, 0xbfb8aa3b, v132
	v_exp_f32_e32 v132, v132
	v_cvt_pk_bf16_f32 v126, v130, v126
	s_waitcnt vmcnt(0)
	v_lshlrev_b32_e32 v134, 16, v122
	v_and_b32_e32 v122, 0xffff0000, v122
	v_add_f32_e32 v132, 1.0, v132
	v_rcp_f32_e32 v132, v132
	s_nop 0
	v_mul_f32_e32 v131, v132, v131
	v_mul_f32_e32 v132, v135, v127
	v_fmac_f32_e32 v127, v133, v127
	v_mul_f32_e32 v127, 0x3fcc422a, v127
	v_mul_f32_e32 v127, 0xbfb8aa3b, v127
	v_exp_f32_e32 v127, v127
	v_lshlrev_b32_e32 v133, 16, v121
	v_and_b32_e32 v121, 0xffff0000, v121
	v_lshlrev_b32_e32 v135, 16, v123
	v_add_f32_e32 v127, 1.0, v127
	v_rcp_f32_e32 v127, v127
	v_and_b32_e32 v123, 0xffff0000, v123
	v_mul_f32_e32 v127, v127, v132
	v_cvt_pk_bf16_f32 v127, v131, v127
	global_store_dwordx4 v[128:129], v[124:127], off
	ds_read_b128 v[124:127], v228 offset:4480
	ds_read_b128 v[128:131], v228 offset:4496
	v_lshlrev_b32_e32 v132, 16, v120
	v_mul_f32_e32 v136, 0x3d372713, v132
	v_mul_f32_e32 v136, v136, v132
	s_waitcnt lgkmcnt(1)
	v_mul_f32_e32 v124, v124, v132
	v_fmac_f32_e32 v132, v136, v132
	v_mul_f32_e32 v132, 0x3fcc422a, v132
	v_mul_f32_e32 v132, 0xbfb8aa3b, v132
	v_exp_f32_e32 v132, v132
	v_and_b32_e32 v120, 0xffff0000, v120
	v_mul_f32_e32 v125, v125, v120
	v_add_f32_e32 v132, 1.0, v132
	v_rcp_f32_e32 v132, v132
	s_nop 0
	v_mul_f32_e32 v124, v132, v124
	v_mul_f32_e32 v132, 0x3d372713, v120
	v_mul_f32_e32 v132, v132, v120
	v_fmac_f32_e32 v120, v132, v120
	v_mul_f32_e32 v120, 0x3fcc422a, v120
	v_mul_f32_e32 v120, 0xbfb8aa3b, v120
	v_exp_f32_e32 v120, v120
	s_nop 0
	v_add_f32_e32 v120, 1.0, v120
	v_rcp_f32_e32 v120, v120
	s_nop 0
	v_mul_f32_e32 v120, v120, v125
	v_mul_f32_e32 v125, v126, v133
	v_mul_f32_e32 v126, 0x3d372713, v133
	v_mul_f32_e32 v126, v126, v133
	v_fmac_f32_e32 v133, v126, v133
	v_mul_f32_e32 v126, 0x3fcc422a, v133
	v_mul_f32_e32 v126, 0xbfb8aa3b, v126
	v_exp_f32_e32 v126, v126
	v_cvt_pk_bf16_f32 v120, v124, v120
	s_nop 0
	v_add_f32_e32 v126, 1.0, v126
	v_rcp_f32_e32 v126, v126
	s_nop 0
	v_mul_f32_e32 v125, v126, v125
	v_mul_f32_e32 v126, v127, v121
	v_mul_f32_e32 v127, 0x3d372713, v121
	v_mul_f32_e32 v127, v127, v121
	v_fmac_f32_e32 v121, v127, v121
	v_mul_f32_e32 v121, 0x3fcc422a, v121
	v_mul_f32_e32 v121, 0xbfb8aa3b, v121
	v_exp_f32_e32 v121, v121
	v_mul_f32_e32 v127, 0x3d372713, v134
	v_mul_f32_e32 v127, v127, v134
	v_add_f32_e32 v121, 1.0, v121
	v_rcp_f32_e32 v121, v121
	s_nop 0
	v_mul_f32_e32 v121, v121, v126
	s_waitcnt lgkmcnt(0)
	v_mul_f32_e32 v126, v128, v134
	v_fmac_f32_e32 v134, v127, v134
	v_mul_f32_e32 v127, 0x3fcc422a, v134
	v_mul_f32_e32 v127, 0xbfb8aa3b, v127
	v_exp_f32_e32 v127, v127
	v_mul_f32_e32 v128, 0x3d372713, v122
	v_mul_f32_e32 v128, v128, v122
	v_cvt_pk_bf16_f32 v121, v125, v121
	v_add_f32_e32 v127, 1.0, v127
	v_rcp_f32_e32 v127, v127
	v_lshl_add_u64 v[124:125], v[178:179], 0, v[166:167]
	v_lshl_add_u64 v[178:179], v[178:179], 0, s[60:61]
	v_mul_f32_e32 v126, v127, v126
	v_mul_f32_e32 v127, v129, v122
	v_fmac_f32_e32 v122, v128, v122
	v_mul_f32_e32 v122, 0x3fcc422a, v122
	v_mul_f32_e32 v122, 0xbfb8aa3b, v122
	v_exp_f32_e32 v122, v122
	v_mul_f32_e32 v128, 0x3d372713, v135
	v_mul_f32_e32 v128, v128, v135
	v_mul_f32_e32 v129, 0x3d372713, v123
	v_add_f32_e32 v122, 1.0, v122
	v_rcp_f32_e32 v122, v122
	v_mul_f32_e32 v129, v129, v123
	v_mul_f32_e32 v122, v122, v127
	v_mul_f32_e32 v127, v130, v135
	v_fmac_f32_e32 v135, v128, v135
	v_mul_f32_e32 v128, 0x3fcc422a, v135
	v_mul_f32_e32 v128, 0xbfb8aa3b, v128
	v_exp_f32_e32 v128, v128
	v_cvt_pk_bf16_f32 v122, v126, v122
	s_nop 0
	v_add_f32_e32 v128, 1.0, v128
	v_rcp_f32_e32 v128, v128
	s_nop 0
	v_mul_f32_e32 v127, v128, v127
	v_mul_f32_e32 v128, v131, v123
	v_fmac_f32_e32 v123, v129, v123
	v_mul_f32_e32 v123, 0x3fcc422a, v123
	v_mul_f32_e32 v123, 0xbfb8aa3b, v123
	v_exp_f32_e32 v123, v123
	s_nop 0
	v_add_f32_e32 v123, 1.0, v123
	v_rcp_f32_e32 v123, v123
	s_nop 0
	v_mul_f32_e32 v123, v123, v128
	v_cvt_pk_bf16_f32 v123, v127, v123
	global_store_dwordx4 v[124:125], v[120:123], off
	s_waitcnt lgkmcnt(0)
	s_cbranch_scc0 .LBB0_249
